# XCD-local grid barrier: each workgroup stores the barrier index into its own word of a per-XCD 128-byte flag line (plain store, stays in L2) and 32 lanes poll the whole line (no atomics)
# speedup vs baseline: 1.0086x; 1.0086x over previous
.LBB0_498:
	s_waitcnt vmcnt(0)
	s_barrier
	s_and_saveexec_b64 s[4:5], s[10:11]
	s_cbranch_execz .LBB0_550
	s_add_i32 s6, 0, 0x20160
	v_mov_b32_e32 v0, s6
	s_waitcnt vmcnt(0) expcnt(0) lgkmcnt(0)
	s_cmp_eq_u32 s98, 0
	s_cbranch_scc1 .Leinv_1
	buffer_inv sc1
	s_and_b32 s99, s2, 7
	s_lshl_b32 s99, s99, 8
	s_add_u32 s99, s99, 0xd000
	s_lshr_b32 s6, s2, 3
	s_lshl_b32 s6, s6, 2
	s_add_u32 s6, s6, s99
	v_mov_b32_e32 v0, s6
	v_mov_b32_e32 v1, 1
	global_store_dword v0, v1, s[52:53]
	s_mov_b32 exec_lo, -1
	s_mov_b32 exec_hi, 0
	v_mbcnt_lo_u32_b32 v3, -1, 0
	v_lshl_add_u32 v3, v3, 2, s99
.Lfb_poll_1:
	global_load_dword v2, v3, s[52:53] sc1
	s_waitcnt vmcnt(0)
	v_cmp_gt_u32_e32 vcc, 1, v2
	s_cbranch_vccz .Lfb_done_1
	s_sleep 1
	s_branch .Lfb_poll_1

.LBB0_558:
	s_barrier
	s_waitcnt vmcnt(0)
	s_barrier
	s_and_saveexec_b64 s[4:5], s[10:11]
	s_cbranch_execz .LBB0_610
	s_add_i32 s6, 0, 0x20160
	s_waitcnt vmcnt(12)
	v_mov_b32_e32 v0, s6
	s_waitcnt vmcnt(0) expcnt(0) lgkmcnt(0)
	s_cmp_eq_u32 s98, 0
	s_cbranch_scc1 .Leinv_2
	buffer_inv sc1
	s_and_b32 s99, s2, 7
	s_lshl_b32 s99, s99, 8
	s_add_u32 s99, s99, 0xd000
	s_lshr_b32 s6, s2, 3
	s_lshl_b32 s6, s6, 2
	s_add_u32 s6, s6, s99
	v_mov_b32_e32 v0, s6
	v_mov_b32_e32 v1, 2
	global_store_dword v0, v1, s[52:53]
	s_mov_b32 exec_lo, -1
	s_mov_b32 exec_hi, 0
	v_mbcnt_lo_u32_b32 v3, -1, 0
	v_lshl_add_u32 v3, v3, 2, s99
.Lfb_poll_2:
	global_load_dword v2, v3, s[52:53] sc1
	s_waitcnt vmcnt(0)
	v_cmp_gt_u32_e32 vcc, 2, v2
	s_cbranch_vccz .Lfb_done_2
	s_sleep 1
	s_branch .Lfb_poll_2

.LBB0_621:
	s_waitcnt vmcnt(0)
	s_barrier
	s_and_saveexec_b64 s[4:5], s[10:11]
	s_cbranch_execz .LBB0_673
	s_add_i32 s6, 0, 0x20160
	s_waitcnt vmcnt(23)
	v_mov_b32_e32 v0, s6
	s_waitcnt vmcnt(0) expcnt(0) lgkmcnt(0)
	s_cmp_eq_u32 s98, 0
	s_cbranch_scc1 .Leinv_3
	buffer_inv sc1
	s_and_b32 s99, s2, 7
	s_lshl_b32 s99, s99, 8
	s_add_u32 s99, s99, 0xd000
	s_lshr_b32 s6, s2, 3
	s_lshl_b32 s6, s6, 2
	s_add_u32 s6, s6, s99
	v_mov_b32_e32 v0, s6
	v_mov_b32_e32 v1, 3
	global_store_dword v0, v1, s[52:53]
	s_mov_b32 exec_lo, -1
	s_mov_b32 exec_hi, 0
	v_mbcnt_lo_u32_b32 v3, -1, 0
	v_lshl_add_u32 v3, v3, 2, s99
.Lfb_poll_3:
	global_load_dword v2, v3, s[52:53] sc1
	s_waitcnt vmcnt(0)
	v_cmp_gt_u32_e32 vcc, 3, v2
	s_cbranch_vccz .Lfb_done_3
	s_sleep 1
	s_branch .Lfb_poll_3

.LBB0_723:
	s_waitcnt vmcnt(0)
	s_waitcnt lgkmcnt(0)
	s_barrier
	s_and_saveexec_b64 s[4:5], s[10:11]
	s_cbranch_execz .LBB0_775
	s_add_i32 s6, 0, 0x20160
	v_mov_b32_e32 v0, s6
	s_waitcnt vmcnt(0) expcnt(0) lgkmcnt(0)
	s_cmp_eq_u32 s98, 0
	s_cbranch_scc1 .Leinv_4
	buffer_inv sc1
	s_and_b32 s99, s2, 7
	s_lshl_b32 s99, s99, 8
	s_add_u32 s99, s99, 0xd000
	s_lshr_b32 s6, s2, 3
	s_lshl_b32 s6, s6, 2
	s_add_u32 s6, s6, s99
	v_mov_b32_e32 v0, s6
	v_mov_b32_e32 v1, 4
	global_store_dword v0, v1, s[52:53]
	s_mov_b32 exec_lo, -1
	s_mov_b32 exec_hi, 0
	v_mbcnt_lo_u32_b32 v3, -1, 0
	v_lshl_add_u32 v3, v3, 2, s99
.Lfb_poll_4:
	global_load_dword v2, v3, s[52:53] sc1
	s_waitcnt vmcnt(0)
	v_cmp_gt_u32_e32 vcc, 4, v2
	s_cbranch_vccz .Lfb_done_4
	s_sleep 1
	s_branch .Lfb_poll_4

.LBB0_791:
	s_waitcnt vmcnt(0)
	s_barrier
	s_and_saveexec_b64 s[4:5], s[10:11]
	s_cbranch_execz .LBB0_843
	s_add_i32 s6, 0, 0x20160
	v_mov_b32_e32 v0, s6
	s_waitcnt vmcnt(0) expcnt(0) lgkmcnt(0)
	s_cmp_eq_u32 s98, 0
	s_cbranch_scc1 .Leinv_5
	buffer_inv sc1
	s_and_b32 s99, s2, 7
	s_lshl_b32 s99, s99, 8
	s_add_u32 s99, s99, 0xd000
	s_lshr_b32 s6, s2, 3
	s_lshl_b32 s6, s6, 2
	s_add_u32 s6, s6, s99
	v_mov_b32_e32 v0, s6
	v_mov_b32_e32 v1, 5
	global_store_dword v0, v1, s[52:53]
	s_mov_b32 exec_lo, -1
	s_mov_b32 exec_hi, 0
	v_mbcnt_lo_u32_b32 v3, -1, 0
	v_lshl_add_u32 v3, v3, 2, s99
.Lfb_poll_5:
	global_load_dword v2, v3, s[52:53] sc1
	s_waitcnt vmcnt(0)
	v_cmp_gt_u32_e32 vcc, 5, v2
	s_cbranch_vccz .Lfb_done_5
	s_sleep 1
	s_branch .Lfb_poll_5

.LBB0_889:
	s_waitcnt vmcnt(0)
	s_waitcnt lgkmcnt(0)
	s_barrier
	s_and_saveexec_b64 s[4:5], s[10:11]
	s_cbranch_execz .LBB0_941
	s_add_i32 s6, 0, 0x20160
	v_mov_b32_e32 v0, s6
	s_waitcnt vmcnt(0) expcnt(0) lgkmcnt(0)
	s_cmp_eq_u32 s98, 0
	s_cbranch_scc1 .Leinv_6
	buffer_inv sc1
	s_and_b32 s99, s2, 7
	s_lshl_b32 s99, s99, 8
	s_add_u32 s99, s99, 0xd000
	s_lshr_b32 s6, s2, 3
	s_lshl_b32 s6, s6, 2
	s_add_u32 s6, s6, s99
	v_mov_b32_e32 v0, s6
	v_mov_b32_e32 v1, 6
	global_store_dword v0, v1, s[52:53]
	s_mov_b32 exec_lo, -1
	s_mov_b32 exec_hi, 0
	v_mbcnt_lo_u32_b32 v3, -1, 0
	v_lshl_add_u32 v3, v3, 2, s99
.Lfb_poll_6:
	global_load_dword v2, v3, s[52:53] sc1
	s_waitcnt vmcnt(0)
	v_cmp_gt_u32_e32 vcc, 6, v2
	s_cbranch_vccz .Lfb_done_6
	s_sleep 1
	s_branch .Lfb_poll_6

.LBB0_999:
	s_waitcnt vmcnt(0)
	s_barrier
	s_and_saveexec_b64 s[4:5], s[10:11]
	s_cbranch_execz .LBB0_1051
	s_add_i32 s6, 0, 0x20160
	v_mov_b32_e32 v0, s6
	s_waitcnt vmcnt(0) expcnt(0) lgkmcnt(0)
	s_cmp_eq_u32 s98, 0
	s_cbranch_scc1 .Leinv_7
	buffer_inv sc1
	s_and_b32 s99, s2, 7
	s_lshl_b32 s99, s99, 8
	s_add_u32 s99, s99, 0xd000
	s_lshr_b32 s6, s2, 3
	s_lshl_b32 s6, s6, 2
	s_add_u32 s6, s6, s99
	v_mov_b32_e32 v0, s6
	v_mov_b32_e32 v1, 7
	global_store_dword v0, v1, s[52:53]
	s_mov_b32 exec_lo, -1
	s_mov_b32 exec_hi, 0
	v_mbcnt_lo_u32_b32 v3, -1, 0
	v_lshl_add_u32 v3, v3, 2, s99
.Lfb_poll_7:
	global_load_dword v2, v3, s[52:53] sc1
	s_waitcnt vmcnt(0)
	v_cmp_gt_u32_e32 vcc, 7, v2
	s_cbranch_vccz .Lfb_done_7
	s_sleep 1
	s_branch .Lfb_poll_7

.LBB0_1075:
	s_waitcnt vmcnt(0)
	s_barrier
	s_and_saveexec_b64 s[4:5], s[10:11]
	s_cbranch_execz .LBB0_1127
	s_add_i32 s6, 0, 0x20160
	v_mov_b32_e32 v0, s6
	s_waitcnt vmcnt(0) expcnt(0) lgkmcnt(0)
	s_cmp_eq_u32 s98, 0
	s_cbranch_scc1 .Leinv_8
	buffer_inv sc1
	s_and_b32 s99, s2, 7
	s_lshl_b32 s99, s99, 8
	s_add_u32 s99, s99, 0xd000
	s_lshr_b32 s6, s2, 3
	s_lshl_b32 s6, s6, 2
	s_add_u32 s6, s6, s99
	v_mov_b32_e32 v0, s6
	v_mov_b32_e32 v1, 8
	global_store_dword v0, v1, s[52:53]
	s_mov_b32 exec_lo, -1
	s_mov_b32 exec_hi, 0
	v_mbcnt_lo_u32_b32 v3, -1, 0
	v_lshl_add_u32 v3, v3, 2, s99
.Lfb_poll_8:
	global_load_dword v2, v3, s[52:53] sc1
	s_waitcnt vmcnt(0)
	v_cmp_gt_u32_e32 vcc, 8, v2
	s_cbranch_vccz .Lfb_done_8
	s_sleep 1
	s_branch .Lfb_poll_8

.LBB0_1169:
	s_waitcnt vmcnt(0)
	s_waitcnt lgkmcnt(0)
	s_barrier
	s_and_saveexec_b64 s[4:5], s[10:11]
	s_cbranch_execz .LBB0_1221
	s_add_i32 s6, 0, 0x20160
	v_mov_b32_e32 v0, s6
	s_waitcnt vmcnt(0) expcnt(0) lgkmcnt(0)
	s_cmp_eq_u32 s98, 0
	s_cbranch_scc1 .Leinv_9
	buffer_inv sc1
	s_and_b32 s99, s2, 7
	s_lshl_b32 s99, s99, 8
	s_add_u32 s99, s99, 0xd000
	s_lshr_b32 s6, s2, 3
	s_lshl_b32 s6, s6, 2
	s_add_u32 s6, s6, s99
	v_mov_b32_e32 v0, s6
	v_mov_b32_e32 v1, 9
	global_store_dword v0, v1, s[52:53]
	s_mov_b32 exec_lo, -1
	s_mov_b32 exec_hi, 0
	v_mbcnt_lo_u32_b32 v3, -1, 0
	v_lshl_add_u32 v3, v3, 2, s99
.Lfb_poll_9:
	global_load_dword v2, v3, s[52:53] sc1
	s_waitcnt vmcnt(0)
	v_cmp_gt_u32_e32 vcc, 9, v2
	s_cbranch_vccz .Lfb_done_9
	s_sleep 1
	s_branch .Lfb_poll_9

.LBB0_1237:
	s_waitcnt vmcnt(0)
	s_barrier
	s_and_saveexec_b64 s[4:5], s[10:11]
	s_cbranch_execz .LBB0_1289
	s_add_i32 s6, 0, 0x20160
	v_mov_b32_e32 v0, s6
	s_waitcnt vmcnt(0) expcnt(0) lgkmcnt(0)
	s_cmp_eq_u32 s98, 0
	s_cbranch_scc1 .Leinv_10
	buffer_inv sc1
	s_and_b32 s99, s2, 7
	s_lshl_b32 s99, s99, 8
	s_add_u32 s99, s99, 0xd000
	s_lshr_b32 s6, s2, 3
	s_lshl_b32 s6, s6, 2
	s_add_u32 s6, s6, s99
	v_mov_b32_e32 v0, s6
	v_mov_b32_e32 v1, 10
	global_store_dword v0, v1, s[52:53]
	s_mov_b32 exec_lo, -1
	s_mov_b32 exec_hi, 0
	v_mbcnt_lo_u32_b32 v3, -1, 0
	v_lshl_add_u32 v3, v3, 2, s99
.Lfb_poll_10:
	global_load_dword v2, v3, s[52:53] sc1
	s_waitcnt vmcnt(0)
	v_cmp_gt_u32_e32 vcc, 10, v2
	s_cbranch_vccz .Lfb_done_10
	s_sleep 1
	s_branch .Lfb_poll_10
